# QKV K-loop: removed the compiler's per-iteration vmcnt(0) (row-stat loads it guarded are already waited after the epilogue), restoring the counted DMA pipeline
# speedup vs baseline: 1.0040x; 1.0040x over previous
; #define PG8_STAGE(bufoff, gbase, voff) do { _Pragma("unroll") for (int _i = 0; _i < 2; ++_i) \
;         __builtin_amdgcn_global_load_lds((const unsigned*)((const char*)(gbase) + (voff)[_i]), (LAS unsigned*)(lds + (bufoff) + ldsw + _i * 8192), 16, 0, 0); } while (0)
; #define PG8_LDA(dst, b, h) do { _Pragma("unroll") for (int m = 0; m < 4; ++m) _Pragma("unroll") for (int k = 0; k < 2; ++k) dst[m][k] = *(const LAS bf16x8*)(lds + PG8_SA(b, h) + aoff + m * 2048 + k * 1024); } while (0)
; #define PG8_LDB(dst, b, h) do { _Pragma("unroll") for (int n = 0; n < 2; ++n) _Pragma("unroll") for (int k = 0; k < 2; ++k) dst[n][k] = *(const LAS bf16x8*)(lds + PG8_SB(b, h) + boff + n * 2048 + k * 1024); } while (0)
; #define PG8_MMA(ai, bj, At, Bt) do { __builtin_amdgcn_s_setprio(1); _Pragma("unroll") for (int m = 0; m < 4; ++m) _Pragma("unroll") for (int n = 0; n < 2; ++n) _Pragma("unroll") for (int k = 0; k < 2; ++k) \
;         acc[ai][bj][m][n] = __builtin_amdgcn_mfma_f32_16x16x32_bf16(Bt[n][k], At[m][k], acc[ai][bj][m][n], 0, 0, 0); __builtin_amdgcn_s_setprio(0); } while (0)
; #define PG8_WAIT_V(n) asm volatile("s_waitcnt vmcnt(" #n ")" ::: "memory")
; #define PG8_WAIT_L(n) asm volatile("s_waitcnt lgkmcnt(" #n ")" ::: "memory")
; #define PG8_BAR __builtin_amdgcn_s_barrier()
; #define PG8_SCHED __builtin_amdgcn_sched_barrier(0)
; template <class Epi, bool ALIGN_EPI>
; __device__ __forceinline__ void gemm_phase(LAS unsigned char* lds, const Gemm g, int G, int cid, const Epi& E) {
;     ...
;             const char* a1 = cA + (size_t)(t + 1) * kA;
;             const char* a2 = last ? nA : cA + (size_t)(t + 2) * kA; const char* b2 = last ? nB : cB + (size_t)(t + 2) * kB;
;             const char* a3 = a2 + kA; const char* b3 = b2 + kB;
;             PG8_LDB(B0, 0, 0); PG8_LDB(B1, 0, 1); PG8_SCHED; PG8_LDA(At, 0, 0); PG8_STAGE(PG8_SA(1, 1), a1 + hA, voffA);
;             PG8_WAIT_V(8); PG8_WAIT_L(0); PG8_BAR; PG8_MMA(0, 0, At, B0); PG8_MMA(0, 1, At, B1); PG8_BAR; PG8_SCHED;
;             PG8_LDA(At, 0, 1); PG8_STAGE(PG8_SB(0, 0), b2, voffB); PG8_STAGE(PG8_SB(0, 1), b2 + hB, voffB); PG8_STAGE(PG8_SA(0, 0), a2, voffA);
;             PG8_WAIT_V(8); PG8_WAIT_L(0); PG8_BAR; PG8_MMA(1, 0, At, B0); PG8_MMA(1, 1, At, B1); PG8_BAR; PG8_SCHED;
.LBB0_266:
	s_add_u32 s74, s72, 0x100
	s_addc_u32 s75, s73, 0
	s_and_b64 s[58:59], exec, s[58:59]
	s_cselect_b32 s59, s49, s75
	s_cselect_b32 s58, s48, s74
	s_add_i32 s6, 0, 0x10000
	s_add_i32 s7, 0, 0x14000
	v_add_u32_e32 v108, s6, v190
	v_add_u32_e32 v132, s7, v190
	ds_read_b128 v[88:91], v108
	ds_read_b128 v[100:103], v108 offset:1024
	ds_read_b128 v[104:107], v108 offset:2048
	ds_read_b128 v[108:111], v108 offset:3072
	ds_read_b128 v[112:115], v132
	ds_read_b128 v[120:123], v132 offset:1024
	ds_read_b128 v[124:127], v132 offset:2048
	ds_read_b128 v[132:135], v132 offset:3072
	v_lshl_add_u64 v[198:199], s[72:73], 0, v[178:179]
	s_add_i32 m0, s23, 0xc000
	ds_read_b128 v[164:167], v222
	ds_read_b128 v[168:171], v222 offset:1024
	ds_read_b128 v[182:185], v222 offset:2048
	ds_read_b128 v[224:227], v222 offset:3072
	ds_read_b128 v[228:231], v222 offset:4096
	ds_read_b128 v[232:235], v222 offset:5120
	ds_read_b128 v[244:247], v222 offset:6144
	ds_read_b128 v[248:251], v222 offset:7168
	global_load_lds_dwordx4 v[198:199], off
	v_lshl_add_u64 v[198:199], s[72:73], 0, v[180:181]
	s_add_i32 m0, s23, 0xe000
	s_nop 0
	global_load_lds_dwordx4 v[198:199], off
	s_waitcnt vmcnt(8)
	s_waitcnt lgkmcnt(0)
	s_barrier
	s_setprio 1
	s_waitcnt lgkmcnt(0)
	v_mfma_f32_16x16x32_bf16 v[160:163], v[88:91], v[164:167], v[160:163]
	v_mfma_f32_16x16x32_bf16 v[156:159], v[104:107], v[164:167], v[156:159]
	v_mfma_f32_16x16x32_bf16 v[144:147], v[88:91], v[182:185], v[144:147]
	v_mfma_f32_16x16x32_bf16 v[140:143], v[104:107], v[182:185], v[140:143]
	v_mfma_f32_16x16x32_bf16 v[96:99], v[88:91], v[228:231], v[96:99]
	v_mfma_f32_16x16x32_bf16 v[92:95], v[104:107], v[228:231], v[92:95]
	v_mfma_f32_16x16x32_bf16 v[76:79], v[88:91], v[244:247], v[76:79]
	v_mfma_f32_16x16x32_bf16 v[72:75], v[104:107], v[244:247], v[72:75]
	v_mfma_f32_16x16x32_bf16 v[160:163], v[100:103], v[168:171], v[160:163]
	v_mfma_f32_16x16x32_bf16 v[156:159], v[108:111], v[168:171], v[156:159]
	v_mfma_f32_16x16x32_bf16 v[144:147], v[100:103], v[224:227], v[144:147]
	v_mfma_f32_16x16x32_bf16 v[140:143], v[108:111], v[224:227], v[140:143]
	v_mfma_f32_16x16x32_bf16 v[96:99], v[100:103], v[232:235], v[96:99]
	v_mfma_f32_16x16x32_bf16 v[92:95], v[108:111], v[232:235], v[92:95]
	v_mfma_f32_16x16x32_bf16 v[76:79], v[100:103], v[248:251], v[76:79]
	v_mfma_f32_16x16x32_bf16 v[72:75], v[108:111], v[248:251], v[72:75]
	s_setprio 0
	s_setprio 1
	v_mfma_f32_16x16x32_bf16 v[152:155], v[112:115], v[164:167], v[152:155]
	v_mfma_f32_16x16x32_bf16 v[148:151], v[124:127], v[164:167], v[148:151]
	v_mfma_f32_16x16x32_bf16 v[128:131], v[112:115], v[182:185], v[128:131]
	v_mfma_f32_16x16x32_bf16 v[116:119], v[124:127], v[182:185], v[116:119]
	v_mfma_f32_16x16x32_bf16 v[84:87], v[112:115], v[228:231], v[84:87]
	v_mfma_f32_16x16x32_bf16 v[80:83], v[124:127], v[228:231], v[80:83]
	v_mfma_f32_16x16x32_bf16 v[68:71], v[112:115], v[244:247], v[68:71]
	v_mfma_f32_16x16x32_bf16 v[64:67], v[124:127], v[244:247], v[64:67]
	v_mfma_f32_16x16x32_bf16 v[152:155], v[120:123], v[168:171], v[152:155]
	v_mfma_f32_16x16x32_bf16 v[148:151], v[132:135], v[168:171], v[148:151]
	v_mfma_f32_16x16x32_bf16 v[128:131], v[120:123], v[224:227], v[128:131]
	v_mfma_f32_16x16x32_bf16 v[116:119], v[132:135], v[224:227], v[116:119]
	v_mfma_f32_16x16x32_bf16 v[84:87], v[120:123], v[232:235], v[84:87]
	v_mfma_f32_16x16x32_bf16 v[80:83], v[132:135], v[232:235], v[80:83]
	v_mfma_f32_16x16x32_bf16 v[68:71], v[120:123], v[248:251], v[68:71]
	v_mfma_f32_16x16x32_bf16 v[64:67], v[132:135], v[248:251], v[64:67]
	s_setprio 0
	s_barrier
	s_add_i32 s6, s6, s0
	v_lshl_add_u64 v[198:199], s[56:57], 0, v[172:173]
	s_mov_b32 m0, s6
	ds_read_b128 v[164:167], v222 offset:16384
	ds_read_b128 v[168:171], v222 offset:17408
	ds_read_b128 v[182:185], v222 offset:18432
	ds_read_b128 v[224:227], v222 offset:19456
	ds_read_b128 v[228:231], v222 offset:20480
	ds_read_b128 v[232:235], v222 offset:21504
	ds_read_b128 v[244:247], v222 offset:22528
	ds_read_b128 v[248:251], v222 offset:23552
	global_load_lds_dwordx4 v[198:199], off
	s_add_i32 m0, s6, 0x2000
	s_add_u32 s72, s56, 0x2000
	v_lshl_add_u64 v[198:199], s[56:57], 0, v[176:177]
	s_addc_u32 s73, s57, 0
	s_add_i32 s6, s7, s0
	global_load_lds_dwordx4 v[198:199], off
	v_lshl_add_u64 v[198:199], s[72:73], 0, v[172:173]
	s_mov_b32 m0, s6
	v_lshl_add_u64 v[200:201], s[58:59], 0, v[174:175]
	global_load_lds_dwordx4 v[198:199], off
	v_lshl_add_u64 v[198:199], s[72:73], 0, v[176:177]
	s_add_i32 m0, s6, 0x2000
	s_nop 0
	global_load_lds_dwordx4 v[198:199], off
	v_lshl_add_u64 v[198:199], s[58:59], 0, v[136:137]
	s_mov_b32 m0, s23
	s_nop 0
	global_load_lds_dwordx4 v[198:199], off
	s_mov_b32 m0, s24
	s_nop 0
	global_load_lds_dwordx4 v[200:201], off
	s_waitcnt vmcnt(8)
	s_waitcnt lgkmcnt(0)
	s_barrier
; #define PG8_STAGE(bufoff, gbase, voff) do { _Pragma("unroll") for (int _i = 0; _i < 2; ++_i) \
;         __builtin_amdgcn_global_load_lds((const unsigned*)((const char*)(gbase) + (voff)[_i]), (LAS unsigned*)(lds + (bufoff) + ldsw + _i * 8192), 16, 0, 0); } while (0)
; #define PG8_LDA(dst, b, h) do { _Pragma("unroll") for (int m = 0; m < 4; ++m) _Pragma("unroll") for (int k = 0; k < 2; ++k) dst[m][k] = *(const LAS bf16x8*)(lds + PG8_SA(b, h) + aoff + m * 2048 + k * 1024); } while (0)
; #define PG8_LDB(dst, b, h) do { _Pragma("unroll") for (int n = 0; n < 2; ++n) _Pragma("unroll") for (int k = 0; k < 2; ++k) dst[n][k] = *(const LAS bf16x8*)(lds + PG8_SB(b, h) + boff + n * 2048 + k * 1024); } while (0)
; #define PG8_MMA(ai, bj, At, Bt) do { __builtin_amdgcn_s_setprio(1); _Pragma("unroll") for (int m = 0; m < 4; ++m) _Pragma("unroll") for (int n = 0; n < 2; ++n) _Pragma("unroll") for (int k = 0; k < 2; ++k) \
;         acc[ai][bj][m][n] = __builtin_amdgcn_mfma_f32_16x16x32_bf16(Bt[n][k], At[m][k], acc[ai][bj][m][n], 0, 0, 0); __builtin_amdgcn_s_setprio(0); } while (0)
; #define PG8_WAIT_V(n) asm volatile("s_waitcnt vmcnt(" #n ")" ::: "memory")
; #define PG8_WAIT_L(n) asm volatile("s_waitcnt lgkmcnt(" #n ")" ::: "memory")
; #define PG8_BAR __builtin_amdgcn_s_barrier()
; #define PG8_SCHED __builtin_amdgcn_sched_barrier(0)
; template <class Epi, bool ALIGN_EPI>
; __device__ __forceinline__ void gemm_phase(LAS unsigned char* lds, const Gemm g, int G, int cid, const Epi& E) {
;     ...
;             PG8_WAIT_V(8); PG8_WAIT_L(0); PG8_BAR; PG8_MMA(1, 0, At, B0); PG8_MMA(1, 1, At, B1); PG8_BAR; PG8_SCHED;
;             PG8_LDB(B0, 1, 0); PG8_LDB(B1, 1, 1); PG8_SCHED; PG8_LDA(At, 1, 0); PG8_STAGE(PG8_SA(0, 1), a2 + hA, voffA);
;             PG8_WAIT_V(8); PG8_WAIT_L(0); PG8_BAR; PG8_MMA(0, 0, At, B0); PG8_MMA(0, 1, At, B1); PG8_BAR; PG8_SCHED;
	s_setprio 1
	s_waitcnt lgkmcnt(0)
	v_mfma_f32_16x16x32_bf16 v[60:63], v[88:91], v[164:167], v[60:63]
	v_mfma_f32_16x16x32_bf16 v[56:59], v[104:107], v[164:167], v[56:59]
	v_mfma_f32_16x16x32_bf16 v[44:47], v[88:91], v[182:185], v[44:47]
	v_mfma_f32_16x16x32_bf16 v[40:43], v[104:107], v[182:185], v[40:43]
	v_mfma_f32_16x16x32_bf16 v[28:31], v[88:91], v[228:231], v[28:31]
	v_mfma_f32_16x16x32_bf16 v[24:27], v[104:107], v[228:231], v[24:27]
	v_mfma_f32_16x16x32_bf16 v[12:15], v[88:91], v[244:247], v[12:15]
	v_mfma_f32_16x16x32_bf16 v[8:11], v[104:107], v[244:247], v[8:11]
	v_mfma_f32_16x16x32_bf16 v[60:63], v[100:103], v[168:171], v[60:63]
	v_mfma_f32_16x16x32_bf16 v[56:59], v[108:111], v[168:171], v[56:59]
	v_mfma_f32_16x16x32_bf16 v[44:47], v[100:103], v[224:227], v[44:47]
	v_mfma_f32_16x16x32_bf16 v[40:43], v[108:111], v[224:227], v[40:43]
	v_mfma_f32_16x16x32_bf16 v[28:31], v[100:103], v[232:235], v[28:31]
	v_mfma_f32_16x16x32_bf16 v[24:27], v[108:111], v[232:235], v[24:27]
	v_mfma_f32_16x16x32_bf16 v[12:15], v[100:103], v[248:251], v[12:15]
	v_mfma_f32_16x16x32_bf16 v[8:11], v[108:111], v[248:251], v[8:11]
	s_setprio 0
	s_setprio 1
	v_mfma_f32_16x16x32_bf16 v[52:55], v[112:115], v[164:167], v[52:55]
	v_mfma_f32_16x16x32_bf16 v[48:51], v[124:127], v[164:167], v[48:51]
	v_mfma_f32_16x16x32_bf16 v[36:39], v[112:115], v[182:185], v[36:39]
	v_mfma_f32_16x16x32_bf16 v[32:35], v[124:127], v[182:185], v[32:35]
	v_mfma_f32_16x16x32_bf16 v[20:23], v[112:115], v[228:231], v[20:23]
	v_mfma_f32_16x16x32_bf16 v[16:19], v[124:127], v[228:231], v[16:19]
	v_mfma_f32_16x16x32_bf16 v[4:7], v[112:115], v[244:247], v[4:7]
	v_mfma_f32_16x16x32_bf16 v[0:3], v[124:127], v[244:247], v[0:3]
	v_mfma_f32_16x16x32_bf16 v[52:55], v[120:123], v[168:171], v[52:55]
	v_mfma_f32_16x16x32_bf16 v[48:51], v[132:135], v[168:171], v[48:51]
	v_mfma_f32_16x16x32_bf16 v[36:39], v[120:123], v[224:227], v[36:39]
	v_mfma_f32_16x16x32_bf16 v[32:35], v[132:135], v[224:227], v[32:35]
	v_mfma_f32_16x16x32_bf16 v[20:23], v[120:123], v[232:235], v[20:23]
	v_mfma_f32_16x16x32_bf16 v[16:19], v[132:135], v[232:235], v[16:19]
	v_mfma_f32_16x16x32_bf16 v[4:7], v[120:123], v[248:251], v[4:7]
	v_mfma_f32_16x16x32_bf16 v[0:3], v[132:135], v[248:251], v[0:3]
	s_setprio 0
	s_barrier
	s_add_i32 s6, 0, 0x18000
	s_add_i32 s7, 0, 0x1c000
	v_add_u32_e32 v108, s6, v190
	v_add_u32_e32 v132, s7, v190
	ds_read_b128 v[88:91], v108
	ds_read_b128 v[100:103], v108 offset:1024
	ds_read_b128 v[104:107], v108 offset:2048
	ds_read_b128 v[108:111], v108 offset:3072
	ds_read_b128 v[112:115], v132
	ds_read_b128 v[120:123], v132 offset:1024
	ds_read_b128 v[124:127], v132 offset:2048
	ds_read_b128 v[132:135], v132 offset:3072
	s_add_u32 s58, s58, 0x84000
	s_addc_u32 s59, s59, 0
	s_mov_b32 m0, s25
	v_lshl_add_u64 v[242:243], s[58:59], 0, v[136:137]
	ds_read_b128 v[164:167], v222 offset:32768
	ds_read_b128 v[168:171], v222 offset:33792
	ds_read_b128 v[182:185], v222 offset:34816
	ds_read_b128 v[224:227], v222 offset:35840
	ds_read_b128 v[228:231], v222 offset:36864
	ds_read_b128 v[232:235], v222 offset:37888
	ds_read_b128 v[244:247], v222 offset:38912
	ds_read_b128 v[248:251], v222 offset:39936
	global_load_lds_dwordx4 v[242:243], off
	v_lshl_add_u64 v[242:243], s[58:59], 0, v[174:175]
	s_mov_b32 m0, s76
	s_nop 0
	global_load_lds_dwordx4 v[242:243], off
	s_waitcnt vmcnt(8)
	s_waitcnt lgkmcnt(0)
	s_barrier
	s_setprio 1
	s_waitcnt lgkmcnt(0)
	v_mfma_f32_16x16x32_bf16 v[160:163], v[88:91], v[164:167], v[160:163]
	v_mfma_f32_16x16x32_bf16 v[156:159], v[104:107], v[164:167], v[156:159]
	v_mfma_f32_16x16x32_bf16 v[144:147], v[88:91], v[182:185], v[144:147]
	v_mfma_f32_16x16x32_bf16 v[140:143], v[104:107], v[182:185], v[140:143]
	v_mfma_f32_16x16x32_bf16 v[96:99], v[88:91], v[228:231], v[96:99]
	v_mfma_f32_16x16x32_bf16 v[92:95], v[104:107], v[228:231], v[92:95]
	v_mfma_f32_16x16x32_bf16 v[76:79], v[88:91], v[244:247], v[76:79]
	v_mfma_f32_16x16x32_bf16 v[72:75], v[104:107], v[244:247], v[72:75]
	v_mfma_f32_16x16x32_bf16 v[160:163], v[100:103], v[168:171], v[160:163]
	v_mfma_f32_16x16x32_bf16 v[156:159], v[108:111], v[168:171], v[156:159]
	v_mfma_f32_16x16x32_bf16 v[144:147], v[100:103], v[224:227], v[144:147]
	v_mfma_f32_16x16x32_bf16 v[140:143], v[108:111], v[224:227], v[140:143]
	v_mfma_f32_16x16x32_bf16 v[96:99], v[100:103], v[232:235], v[96:99]
	v_mfma_f32_16x16x32_bf16 v[92:95], v[108:111], v[232:235], v[92:95]
	v_mfma_f32_16x16x32_bf16 v[76:79], v[100:103], v[248:251], v[76:79]
	v_mfma_f32_16x16x32_bf16 v[72:75], v[108:111], v[248:251], v[72:75]
	s_setprio 0
	s_setprio 1
	v_mfma_f32_16x16x32_bf16 v[152:155], v[112:115], v[164:167], v[152:155]
	v_mfma_f32_16x16x32_bf16 v[148:151], v[124:127], v[164:167], v[148:151]
	v_mfma_f32_16x16x32_bf16 v[128:131], v[112:115], v[182:185], v[128:131]
	v_mfma_f32_16x16x32_bf16 v[116:119], v[124:127], v[182:185], v[116:119]
	v_mfma_f32_16x16x32_bf16 v[84:87], v[112:115], v[228:231], v[84:87]
	v_mfma_f32_16x16x32_bf16 v[80:83], v[124:127], v[228:231], v[80:83]
	v_mfma_f32_16x16x32_bf16 v[68:71], v[112:115], v[244:247], v[68:71]
	v_mfma_f32_16x16x32_bf16 v[64:67], v[124:127], v[244:247], v[64:67]
	v_mfma_f32_16x16x32_bf16 v[152:155], v[120:123], v[168:171], v[152:155]
	v_mfma_f32_16x16x32_bf16 v[148:151], v[132:135], v[168:171], v[148:151]
	v_mfma_f32_16x16x32_bf16 v[128:131], v[120:123], v[224:227], v[128:131]
	v_mfma_f32_16x16x32_bf16 v[116:119], v[132:135], v[224:227], v[116:119]
	v_mfma_f32_16x16x32_bf16 v[84:87], v[120:123], v[232:235], v[84:87]
	v_mfma_f32_16x16x32_bf16 v[80:83], v[132:135], v[232:235], v[80:83]
	v_mfma_f32_16x16x32_bf16 v[68:71], v[120:123], v[248:251], v[68:71]
	v_mfma_f32_16x16x32_bf16 v[64:67], v[132:135], v[248:251], v[64:67]
	s_setprio 0
	s_barrier
; #define PG8_STAGE(bufoff, gbase, voff) do { _Pragma("unroll") for (int _i = 0; _i < 2; ++_i) \
;         __builtin_amdgcn_global_load_lds((const unsigned*)((const char*)(gbase) + (voff)[_i]), (LAS unsigned*)(lds + (bufoff) + ldsw + _i * 8192), 16, 0, 0); } while (0)
; #define PG8_LDA(dst, b, h) do { _Pragma("unroll") for (int m = 0; m < 4; ++m) _Pragma("unroll") for (int k = 0; k < 2; ++k) dst[m][k] = *(const LAS bf16x8*)(lds + PG8_SA(b, h) + aoff + m * 2048 + k * 1024); } while (0)
; #define PG8_MMA(ai, bj, At, Bt) do { __builtin_amdgcn_s_setprio(1); _Pragma("unroll") for (int m = 0; m < 4; ++m) _Pragma("unroll") for (int n = 0; n < 2; ++n) _Pragma("unroll") for (int k = 0; k < 2; ++k) \
;         acc[ai][bj][m][n] = __builtin_amdgcn_mfma_f32_16x16x32_bf16(Bt[n][k], At[m][k], acc[ai][bj][m][n], 0, 0, 0); __builtin_amdgcn_s_setprio(0); } while (0)
; #define PG8_WAIT_V(n) asm volatile("s_waitcnt vmcnt(" #n ")" ::: "memory")
; #define PG8_WAIT_L(n) asm volatile("s_waitcnt lgkmcnt(" #n ")" ::: "memory")
; #define PG8_BAR __builtin_amdgcn_s_barrier()
; #define PG8_SCHED __builtin_amdgcn_sched_barrier(0)
; template <class Epi, bool ALIGN_EPI>
; __device__ __forceinline__ void gemm_phase(LAS unsigned char* lds, const Gemm g, int G, int cid, const Epi& E) {
;     ...
;         for (int t = 0; t < nt; t += 2) {
;     ...
;             PG8_LDA(At, 1, 1); PG8_STAGE(PG8_SB(1, 0), b3, voffB); PG8_STAGE(PG8_SB(1, 1), b3 + hB, voffB); PG8_STAGE(PG8_SA(1, 0), a3, voffA);
;             PG8_WAIT_V(8); PG8_WAIT_L(0); PG8_BAR; PG8_MMA(1, 0, At, B0); PG8_MMA(1, 1, At, B1); PG8_BAR; PG8_SCHED;
;         }
	s_add_u32 s58, s56, 0xc0000
	s_addc_u32 s59, s57, 0
	s_add_i32 s6, s6, s0
	v_lshl_add_u64 v[242:243], s[58:59], 0, v[172:173]
	s_mov_b32 m0, s6
	ds_read_b128 v[164:167], v222 offset:49152
	ds_read_b128 v[168:171], v222 offset:50176
	ds_read_b128 v[182:185], v222 offset:51200
	ds_read_b128 v[224:227], v222 offset:52224
	ds_read_b128 v[228:231], v222 offset:53248
	ds_read_b128 v[232:235], v222 offset:54272
	ds_read_b128 v[244:247], v222 offset:55296
	ds_read_b128 v[248:251], v222 offset:56320
	global_load_lds_dwordx4 v[242:243], off
	s_add_i32 m0, s6, 0x2000
	s_add_u32 s56, s56, 0xc2000
	v_lshl_add_u64 v[242:243], s[58:59], 0, v[176:177]
	s_addc_u32 s57, s57, 0
	s_add_i32 s6, s7, s0
	global_load_lds_dwordx4 v[242:243], off
	v_lshl_add_u64 v[242:243], s[56:57], 0, v[172:173]
	s_mov_b32 m0, s6
	v_lshl_add_u64 v[198:199], v[198:199], 0, s[36:37]
	global_load_lds_dwordx4 v[242:243], off
	v_lshl_add_u64 v[242:243], s[56:57], 0, v[176:177]
	s_add_i32 m0, s6, 0x2000
	s_nop 0
	global_load_lds_dwordx4 v[242:243], off
	s_mov_b32 m0, s78
	s_nop 0
	global_load_lds_dwordx4 v[198:199], off
	v_lshl_add_u64 v[198:199], v[200:201], 0, s[36:37]
	s_mov_b32 m0, s79
	s_nop 0
	global_load_lds_dwordx4 v[198:199], off
	s_waitcnt vmcnt(8)
	s_waitcnt lgkmcnt(0)
	s_barrier
	s_setprio 1
	s_waitcnt lgkmcnt(0)
	v_mfma_f32_16x16x32_bf16 v[60:63], v[88:91], v[164:167], v[60:63]
	v_mfma_f32_16x16x32_bf16 v[56:59], v[104:107], v[164:167], v[56:59]
	v_mfma_f32_16x16x32_bf16 v[44:47], v[88:91], v[182:185], v[44:47]
	v_mfma_f32_16x16x32_bf16 v[40:43], v[104:107], v[182:185], v[40:43]
	v_mfma_f32_16x16x32_bf16 v[28:31], v[88:91], v[228:231], v[28:31]
	v_mfma_f32_16x16x32_bf16 v[24:27], v[104:107], v[228:231], v[24:27]
	v_mfma_f32_16x16x32_bf16 v[12:15], v[88:91], v[244:247], v[12:15]
	v_mfma_f32_16x16x32_bf16 v[8:11], v[104:107], v[244:247], v[8:11]
	v_mfma_f32_16x16x32_bf16 v[60:63], v[100:103], v[168:171], v[60:63]
	v_mfma_f32_16x16x32_bf16 v[56:59], v[108:111], v[168:171], v[56:59]
	v_mfma_f32_16x16x32_bf16 v[44:47], v[100:103], v[224:227], v[44:47]
	v_mfma_f32_16x16x32_bf16 v[40:43], v[108:111], v[224:227], v[40:43]
	v_mfma_f32_16x16x32_bf16 v[28:31], v[100:103], v[232:235], v[28:31]
	v_mfma_f32_16x16x32_bf16 v[24:27], v[108:111], v[232:235], v[24:27]
	v_mfma_f32_16x16x32_bf16 v[12:15], v[100:103], v[248:251], v[12:15]
	v_mfma_f32_16x16x32_bf16 v[8:11], v[108:111], v[248:251], v[8:11]
	s_setprio 0
	s_setprio 1
	v_mfma_f32_16x16x32_bf16 v[52:55], v[112:115], v[164:167], v[52:55]
	v_mfma_f32_16x16x32_bf16 v[48:51], v[124:127], v[164:167], v[48:51]
	v_mfma_f32_16x16x32_bf16 v[36:39], v[112:115], v[182:185], v[36:39]
	v_mfma_f32_16x16x32_bf16 v[32:35], v[124:127], v[182:185], v[32:35]
	v_mfma_f32_16x16x32_bf16 v[20:23], v[112:115], v[228:231], v[20:23]
	v_mfma_f32_16x16x32_bf16 v[16:19], v[124:127], v[228:231], v[16:19]
	v_mfma_f32_16x16x32_bf16 v[4:7], v[112:115], v[244:247], v[4:7]
	v_mfma_f32_16x16x32_bf16 v[0:3], v[124:127], v[244:247], v[0:3]
	v_mfma_f32_16x16x32_bf16 v[52:55], v[120:123], v[168:171], v[52:55]
	v_mfma_f32_16x16x32_bf16 v[48:51], v[132:135], v[168:171], v[48:51]
	v_mfma_f32_16x16x32_bf16 v[36:39], v[120:123], v[224:227], v[36:39]
	v_mfma_f32_16x16x32_bf16 v[32:35], v[132:135], v[224:227], v[32:35]
	v_mfma_f32_16x16x32_bf16 v[20:23], v[120:123], v[232:235], v[20:23]
	v_mfma_f32_16x16x32_bf16 v[16:19], v[132:135], v[232:235], v[16:19]
	v_mfma_f32_16x16x32_bf16 v[4:7], v[120:123], v[248:251], v[4:7]
	v_mfma_f32_16x16x32_bf16 v[0:3], v[132:135], v[248:251], v[0:3]
	s_setprio 0
	s_barrier
	s_add_i32 s30, s30, 2
	s_add_u32 s54, s54, 0x180000
	s_addc_u32 s55, s55, 0
	s_cmp_gt_u32 s30, 29
	s_mov_b64 s[72:73], s[74:75]
	s_cbranch_scc1 .LBB0_269
